# K=1024 GEMM: first K-loop iteration of each unit peeled with C=0 MFMAs (per-unit zeroing of 128 accumulator registers removed)
# speedup vs baseline: 1.0179x; 1.0034x over previous
; #define PG8_STAGE(bufoff, gbase, voff) do { _Pragma("unroll") for (int _i = 0; _i < 2; ++_i) \
;         __builtin_amdgcn_global_load_lds((const unsigned*)((const char*)(gbase) + (voff)[_i]), (PG8_LAS unsigned*)(lds + (bufoff) + ldsw + _i * 8192), 16, 0, 0); } while (0)
; #define PG8_LDA(dst, b, h) do { _Pragma("unroll") for (int m = 0; m < 4; ++m) _Pragma("unroll") for (int k = 0; k < 2; ++k) dst[m][k] = *(const PG8_LAS bf16x8*)(lds + PG8_SA(b, h) + aoff + m * 2048 + k * 1024); } while (0)
; #define PG8_LDB(dst, b, h) do { _Pragma("unroll") for (int n = 0; n < 2; ++n) _Pragma("unroll") for (int k = 0; k < 2; ++k) dst[n][k] = *(const PG8_LAS bf16x8*)(lds + PG8_SB(b, h) + boff + n * 2048 + k * 1024); } while (0)
; #define PG8_WAIT_V(n) asm volatile("s_waitcnt vmcnt(" #n ")" ::: "memory")
; #define PG8_WAIT_L(n) asm volatile("s_waitcnt lgkmcnt(" #n ")" ::: "memory")
; #define PG8_BAR __builtin_amdgcn_s_barrier()
; #define PG8_SCHED __builtin_amdgcn_sched_barrier(0)
; template <class Epi, class Sched, bool ALIGN_EPI = false, bool SP2 = false>
; __device__ __forceinline__ void gemm_phase(PG8_LAS unsigned char* lds, const Gemm g, const Sched& S, const Epi& E, const int wave0) {
;     ...
;     for (;;) {
;         const bool has_next = S.next(ui + 1, nxt);
;         const char* nA = has_next ? (const char*)g.A + (size_t)nxt.pm * tstep : cA; const char* nB = has_next ? (const char*)g.Bt + (size_t)nxt.pn * tstep : cB;
;         for (int t = 0; t < nt; t += 2) {
;             const bool last = (t == nt - 2);
;             const char* a1 = cA + (size_t)(t + 1) * kstep;
;             const char* a2 = last ? nA : cA + (size_t)(t + 2) * kstep; const char* b2 = last ? nB : cB + (size_t)(t + 2) * kstep;
;             const char* a3 = a2 + kstep; const char* b3 = b2 + kstep;
;             if (last && has_next) S.a_ready(nxt);
;             if constexpr (SP2) {
;             PG8_LDB(B0, 0, 0); PG8_LDB(B1, 0, 1); PG8_SCHED; PG8_LDA(At, 0, 0); PG8_STAGE(PG8_SA(1, 1), a1 + hstep, voffA);
;             PG8_WAIT_V(8); PG8_WAIT_L(0); PG8_BAR; PG8_MMA(0, 0, At, B0); PG8_MMA(0, 1, At, B1); PG8_BAR; PG8_SCHED;
;             PG8_LDA(At, 0, 1); PG8_STAGE(PG8_SB(0, 0), b2, voffB); PG8_STAGE(PG8_SB(0, 1), b2 + hstep, voffB); PG8_STAGE(PG8_SA(0, 0), a2, voffA);
;             PG8_WAIT_V(8); PG8_WAIT_L(0); PG8_BAR; PG8_MMA(1, 0, At, B0); PG8_MMA(1, 1, At, B1); PG8_BAR; PG8_SCHED;
.LBB0_1139:
	s_ashr_i32 s49, s48, 31
	s_lshl_b64 s[18:19], s[48:49], 19
	s_add_u32 s50, s36, s18
	s_addc_u32 s51, s37, s19
	s_and_b64 s[18:19], s[6:7], exec
	s_cselect_b32 s9, s51, s11
	s_cselect_b32 s49, s50, s10
	s_ashr_i32 s47, s46, 31
	s_lshl_b64 s[18:19], s[46:47], 19
	s_add_u32 s52, s38, s18
	s_addc_u32 s53, s39, s19
	s_and_b64 s[18:19], s[6:7], exec
	s_cselect_b32 s47, s53, s57
	s_cselect_b32 s60, s52, s56
	s_add_u32 s10, s10, 0x40080
	s_addc_u32 s11, s11, 0
	s_add_u32 s61, s56, 0x100
	s_addc_u32 s62, s57, 0
	s_mov_b32 s63, -2
	s_waitcnt lgkmcnt(0)
	s_add_u32 s18, s10, 0xfffc0080
	s_addc_u32 s19, s11, -1
	s_add_i32 s64, 0, 0x10000
	s_cmp_eq_u32 s63, 12
	s_cselect_b32 s59, s9, s19
	s_cselect_b32 s58, s49, s18
	s_cselect_b32 s57, s47, s62
	s_cselect_b32 s56, s60, s61
	s_add_i32 s65, 0, 0x14000
	v_add_u32_e32 v140, s64, v247
	v_add_u32_e32 v156, s65, v247
	ds_read_b128 v[64:67], v140
	ds_read_b128 v[68:71], v140 offset:1024
	ds_read_b128 v[136:139], v140 offset:2048
	ds_read_b128 v[140:143], v140 offset:3072
	ds_read_b128 v[144:147], v156
	ds_read_b128 v[148:151], v156 offset:1024
	ds_read_b128 v[152:155], v156 offset:2048
	ds_read_b128 v[156:159], v156 offset:3072
	s_add_i32 m0, s33, 0xc000
	ds_read_b128 v[160:163], v245
	ds_read_b128 v[164:167], v245 offset:1024
	ds_read_b128 v[168:171], v245 offset:2048
	ds_read_b128 v[172:175], v245 offset:3072
	ds_read_b128 v[176:179], v245 offset:4096
	ds_read_b128 v[180:183], v245 offset:5120
	ds_read_b128 v[184:187], v245 offset:6144
	ds_read_b128 v[188:191], v245 offset:7168
	global_load_lds_dwordx4 v224, s[10:11]
	s_add_i32 m0, s33, 0xe000
	s_nop 0
	global_load_lds_dwordx4 v226, s[10:11]
	s_waitcnt vmcnt(8)
	s_waitcnt lgkmcnt(0)
	s_barrier
	s_setprio 1
	v_mfma_f32_16x16x32_bf16 v[132:135], v[64:67], v[160:163], 0
	v_mfma_f32_16x16x32_bf16 v[128:131], v[136:139], v[160:163], 0
	v_mfma_f32_16x16x32_bf16 v[116:119], v[64:67], v[168:171], 0
	v_mfma_f32_16x16x32_bf16 v[108:111], v[136:139], v[168:171], 0
	v_mfma_f32_16x16x32_bf16 v[100:103], v[64:67], v[176:179], 0
	v_mfma_f32_16x16x32_bf16 v[92:95], v[136:139], v[176:179], 0
	v_mfma_f32_16x16x32_bf16 v[84:87], v[64:67], v[184:187], 0
	v_mfma_f32_16x16x32_bf16 v[76:79], v[136:139], v[184:187], 0
	v_mfma_f32_16x16x32_bf16 v[132:135], v[68:71], v[164:167], v[132:135]
	v_mfma_f32_16x16x32_bf16 v[128:131], v[140:143], v[164:167], v[128:131]
	v_mfma_f32_16x16x32_bf16 v[116:119], v[68:71], v[172:175], v[116:119]
	v_mfma_f32_16x16x32_bf16 v[108:111], v[140:143], v[172:175], v[108:111]
	v_mfma_f32_16x16x32_bf16 v[100:103], v[68:71], v[180:183], v[100:103]
	v_mfma_f32_16x16x32_bf16 v[92:95], v[140:143], v[180:183], v[92:95]
	v_mfma_f32_16x16x32_bf16 v[84:87], v[68:71], v[188:191], v[84:87]
	v_mfma_f32_16x16x32_bf16 v[76:79], v[140:143], v[188:191], v[76:79]
	v_mfma_f32_16x16x32_bf16 v[124:127], v[144:147], v[160:163], 0
	v_mfma_f32_16x16x32_bf16 v[120:123], v[152:155], v[160:163], 0
	v_mfma_f32_16x16x32_bf16 v[112:115], v[144:147], v[168:171], 0
	v_mfma_f32_16x16x32_bf16 v[104:107], v[152:155], v[168:171], 0
	v_mfma_f32_16x16x32_bf16 v[96:99], v[144:147], v[176:179], 0
	v_mfma_f32_16x16x32_bf16 v[88:91], v[152:155], v[176:179], 0
	v_mfma_f32_16x16x32_bf16 v[80:83], v[144:147], v[184:187], 0
	v_mfma_f32_16x16x32_bf16 v[72:75], v[152:155], v[184:187], 0
	v_mfma_f32_16x16x32_bf16 v[124:127], v[148:151], v[164:167], v[124:127]
	v_mfma_f32_16x16x32_bf16 v[120:123], v[156:159], v[164:167], v[120:123]
	v_mfma_f32_16x16x32_bf16 v[112:115], v[148:151], v[172:175], v[112:115]
	v_mfma_f32_16x16x32_bf16 v[104:107], v[156:159], v[172:175], v[104:107]
	v_mfma_f32_16x16x32_bf16 v[96:99], v[148:151], v[180:183], v[96:99]
	v_mfma_f32_16x16x32_bf16 v[88:91], v[156:159], v[180:183], v[88:91]
	v_mfma_f32_16x16x32_bf16 v[80:83], v[148:151], v[188:191], v[80:83]
	v_mfma_f32_16x16x32_bf16 v[72:75], v[156:159], v[188:191], v[72:75]
	s_setprio 0
	s_barrier
	s_add_i32 s18, s64, s95
	s_mov_b32 m0, s18
	ds_read_b128 v[160:163], v245 offset:16384
	ds_read_b128 v[164:167], v245 offset:17408
	ds_read_b128 v[168:171], v245 offset:18432
	ds_read_b128 v[172:175], v245 offset:19456
	ds_read_b128 v[176:179], v245 offset:20480
	ds_read_b128 v[180:183], v245 offset:21504
	ds_read_b128 v[184:187], v245 offset:22528
	ds_read_b128 v[188:191], v245 offset:23552
	global_load_lds_dwordx4 v218, s[56:57]
	s_add_i32 m0, s18, 0x2000
	s_add_u32 s18, s56, 0x40000
	s_addc_u32 s19, s57, 0
	s_add_i32 s64, s65, s95
	global_load_lds_dwordx4 v222, s[56:57]
	s_mov_b32 m0, s64
	s_nop 0
	global_load_lds_dwordx4 v218, s[18:19]
	s_add_i32 m0, s64, 0x2000
	s_nop 0
	global_load_lds_dwordx4 v222, s[18:19]
	s_mov_b32 m0, s33
	s_nop 0
	global_load_lds_dwordx4 v216, s[58:59]
	s_mov_b32 m0, s82
	s_nop 0
	global_load_lds_dwordx4 v220, s[58:59]
	s_waitcnt vmcnt(8)
	s_waitcnt lgkmcnt(0)
	s_barrier
; #define PG8_STAGE(bufoff, gbase, voff) do { _Pragma("unroll") for (int _i = 0; _i < 2; ++_i) \
;         __builtin_amdgcn_global_load_lds((const unsigned*)((const char*)(gbase) + (voff)[_i]), (PG8_LAS unsigned*)(lds + (bufoff) + ldsw + _i * 8192), 16, 0, 0); } while (0)
; #define PG8_LDA(dst, b, h) do { _Pragma("unroll") for (int m = 0; m < 4; ++m) _Pragma("unroll") for (int k = 0; k < 2; ++k) dst[m][k] = *(const PG8_LAS bf16x8*)(lds + PG8_SA(b, h) + aoff + m * 2048 + k * 1024); } while (0)
; #define PG8_LDB(dst, b, h) do { _Pragma("unroll") for (int n = 0; n < 2; ++n) _Pragma("unroll") for (int k = 0; k < 2; ++k) dst[n][k] = *(const PG8_LAS bf16x8*)(lds + PG8_SB(b, h) + boff + n * 2048 + k * 1024); } while (0)
; #define PG8_MMA(ai, bj, At, Bt) do { __builtin_amdgcn_s_setprio(1); _Pragma("unroll") for (int m = 0; m < 4; ++m) _Pragma("unroll") for (int n = 0; n < 2; ++n) _Pragma("unroll") for (int k = 0; k < 2; ++k) \
;         acc[ai][bj][m][n] = __builtin_amdgcn_mfma_f32_16x16x32_bf16(Bt[n][k], At[m][k], acc[ai][bj][m][n], 0, 0, 0); __builtin_amdgcn_s_setprio(0); } while (0)
; #define PG8_WAIT_V(n) asm volatile("s_waitcnt vmcnt(" #n ")" ::: "memory")
; #define PG8_WAIT_L(n) asm volatile("s_waitcnt lgkmcnt(" #n ")" ::: "memory")
; #define PG8_BAR __builtin_amdgcn_s_barrier()
; #define PG8_SCHED __builtin_amdgcn_sched_barrier(0)
; template <class Epi, class Sched, bool ALIGN_EPI = false, bool SP2 = false>
; __device__ __forceinline__ void gemm_phase(PG8_LAS unsigned char* lds, const Gemm g, const Sched& S, const Epi& E, const int wave0) {
;     ...
;             PG8_LDB(B0, 0, 0); PG8_LDB(B1, 0, 1); PG8_SCHED; PG8_LDA(At, 0, 0); PG8_STAGE(PG8_SA(1, 1), a1 + hstep, voffA);
;             PG8_WAIT_V(8); PG8_WAIT_L(0); PG8_BAR; PG8_MMA(0, 0, At, B0); PG8_MMA(0, 1, At, B1); PG8_BAR; PG8_SCHED;
;             PG8_LDA(At, 0, 1); PG8_STAGE(PG8_SB(0, 0), b2, voffB); PG8_STAGE(PG8_SB(0, 1), b2 + hstep, voffB); PG8_STAGE(PG8_SA(0, 0), a2, voffA);
;             PG8_WAIT_V(8); PG8_WAIT_L(0); PG8_BAR; PG8_MMA(1, 0, At, B0); PG8_MMA(1, 1, At, B1); PG8_BAR; PG8_SCHED;
;             PG8_LDB(B0, 1, 0); PG8_LDB(B1, 1, 1); PG8_SCHED; PG8_LDA(At, 1, 0); PG8_STAGE(PG8_SA(0, 1), a2 + hstep, voffA);
;             PG8_WAIT_V(8); PG8_WAIT_L(0); PG8_BAR; PG8_MMA(0, 0, At, B0); PG8_MMA(0, 1, At, B1); PG8_BAR; PG8_SCHED;
	s_setprio 1
	v_mfma_f32_16x16x32_bf16 v[60:63], v[64:67], v[160:163], 0
	v_mfma_f32_16x16x32_bf16 v[52:55], v[136:139], v[160:163], 0
	v_mfma_f32_16x16x32_bf16 v[44:47], v[64:67], v[168:171], 0
	v_mfma_f32_16x16x32_bf16 v[36:39], v[136:139], v[168:171], 0
	v_mfma_f32_16x16x32_bf16 v[28:31], v[64:67], v[176:179], 0
	v_mfma_f32_16x16x32_bf16 v[20:23], v[136:139], v[176:179], 0
	v_mfma_f32_16x16x32_bf16 v[12:15], v[64:67], v[184:187], 0
	v_mfma_f32_16x16x32_bf16 v[4:7], v[136:139], v[184:187], 0
	v_mfma_f32_16x16x32_bf16 v[60:63], v[68:71], v[164:167], v[60:63]
	v_mfma_f32_16x16x32_bf16 v[52:55], v[140:143], v[164:167], v[52:55]
	v_mfma_f32_16x16x32_bf16 v[44:47], v[68:71], v[172:175], v[44:47]
	v_mfma_f32_16x16x32_bf16 v[36:39], v[140:143], v[172:175], v[36:39]
	v_mfma_f32_16x16x32_bf16 v[28:31], v[68:71], v[180:183], v[28:31]
	v_mfma_f32_16x16x32_bf16 v[20:23], v[140:143], v[180:183], v[20:23]
	v_mfma_f32_16x16x32_bf16 v[12:15], v[68:71], v[188:191], v[12:15]
	v_mfma_f32_16x16x32_bf16 v[4:7], v[140:143], v[188:191], v[4:7]
	v_mfma_f32_16x16x32_bf16 v[56:59], v[144:147], v[160:163], 0
	v_mfma_f32_16x16x32_bf16 v[48:51], v[152:155], v[160:163], 0
	v_mfma_f32_16x16x32_bf16 v[40:43], v[144:147], v[168:171], 0
	v_mfma_f32_16x16x32_bf16 v[32:35], v[152:155], v[168:171], 0
	v_mfma_f32_16x16x32_bf16 v[24:27], v[144:147], v[176:179], 0
	v_mfma_f32_16x16x32_bf16 v[16:19], v[152:155], v[176:179], 0
	v_mfma_f32_16x16x32_bf16 v[8:11], v[144:147], v[184:187], 0
	v_mfma_f32_16x16x32_bf16 v[0:3], v[152:155], v[184:187], 0
	v_mfma_f32_16x16x32_bf16 v[56:59], v[148:151], v[164:167], v[56:59]
	v_mfma_f32_16x16x32_bf16 v[48:51], v[156:159], v[164:167], v[48:51]
	v_mfma_f32_16x16x32_bf16 v[40:43], v[148:151], v[172:175], v[40:43]
	v_mfma_f32_16x16x32_bf16 v[32:35], v[156:159], v[172:175], v[32:35]
	v_mfma_f32_16x16x32_bf16 v[24:27], v[148:151], v[180:183], v[24:27]
	v_mfma_f32_16x16x32_bf16 v[16:19], v[156:159], v[180:183], v[16:19]
	v_mfma_f32_16x16x32_bf16 v[8:11], v[148:151], v[188:191], v[8:11]
	v_mfma_f32_16x16x32_bf16 v[0:3], v[156:159], v[188:191], v[0:3]
	s_setprio 0
	s_barrier
	s_add_i32 s64, 0, 0x18000
	s_add_i32 s65, 0, 0x1c000
	v_add_u32_e32 v140, s64, v247
	v_add_u32_e32 v156, s65, v247
	ds_read_b128 v[64:67], v140
	ds_read_b128 v[68:71], v140 offset:1024
	ds_read_b128 v[136:139], v140 offset:2048
	ds_read_b128 v[140:143], v140 offset:3072
	ds_read_b128 v[144:147], v156
	ds_read_b128 v[148:151], v156 offset:1024
	ds_read_b128 v[152:155], v156 offset:2048
	ds_read_b128 v[156:159], v156 offset:3072
	s_add_u32 s18, s58, 0x40000
	s_addc_u32 s19, s59, 0
	s_mov_b32 m0, s16
	ds_read_b128 v[160:163], v245 offset:32768
	ds_read_b128 v[164:167], v245 offset:33792
	ds_read_b128 v[168:171], v245 offset:34816
	ds_read_b128 v[172:175], v245 offset:35840
	ds_read_b128 v[176:179], v245 offset:36864
	ds_read_b128 v[180:183], v245 offset:37888
	ds_read_b128 v[184:187], v245 offset:38912
	ds_read_b128 v[188:191], v245 offset:39936
	global_load_lds_dwordx4 v216, s[18:19]
	s_mov_b32 m0, s83
	s_nop 0
	global_load_lds_dwordx4 v220, s[18:19]
	s_waitcnt vmcnt(8)
	s_waitcnt lgkmcnt(0)
	s_barrier
	s_setprio 1
	v_mfma_f32_16x16x32_bf16 v[132:135], v[64:67], v[160:163], v[132:135]
	v_mfma_f32_16x16x32_bf16 v[128:131], v[136:139], v[160:163], v[128:131]
	v_mfma_f32_16x16x32_bf16 v[116:119], v[64:67], v[168:171], v[116:119]
	v_mfma_f32_16x16x32_bf16 v[108:111], v[136:139], v[168:171], v[108:111]
	v_mfma_f32_16x16x32_bf16 v[100:103], v[64:67], v[176:179], v[100:103]
	v_mfma_f32_16x16x32_bf16 v[92:95], v[136:139], v[176:179], v[92:95]
	v_mfma_f32_16x16x32_bf16 v[84:87], v[64:67], v[184:187], v[84:87]
	v_mfma_f32_16x16x32_bf16 v[76:79], v[136:139], v[184:187], v[76:79]
	v_mfma_f32_16x16x32_bf16 v[132:135], v[68:71], v[164:167], v[132:135]
	v_mfma_f32_16x16x32_bf16 v[128:131], v[140:143], v[164:167], v[128:131]
	v_mfma_f32_16x16x32_bf16 v[116:119], v[68:71], v[172:175], v[116:119]
	v_mfma_f32_16x16x32_bf16 v[108:111], v[140:143], v[172:175], v[108:111]
	v_mfma_f32_16x16x32_bf16 v[100:103], v[68:71], v[180:183], v[100:103]
	v_mfma_f32_16x16x32_bf16 v[92:95], v[140:143], v[180:183], v[92:95]
	v_mfma_f32_16x16x32_bf16 v[84:87], v[68:71], v[188:191], v[84:87]
	v_mfma_f32_16x16x32_bf16 v[76:79], v[140:143], v[188:191], v[76:79]
	v_mfma_f32_16x16x32_bf16 v[124:127], v[144:147], v[160:163], v[124:127]
	v_mfma_f32_16x16x32_bf16 v[120:123], v[152:155], v[160:163], v[120:123]
	v_mfma_f32_16x16x32_bf16 v[112:115], v[144:147], v[168:171], v[112:115]
	v_mfma_f32_16x16x32_bf16 v[104:107], v[152:155], v[168:171], v[104:107]
	v_mfma_f32_16x16x32_bf16 v[96:99], v[144:147], v[176:179], v[96:99]
	v_mfma_f32_16x16x32_bf16 v[88:91], v[152:155], v[176:179], v[88:91]
	v_mfma_f32_16x16x32_bf16 v[80:83], v[144:147], v[184:187], v[80:83]
	v_mfma_f32_16x16x32_bf16 v[72:75], v[152:155], v[184:187], v[72:75]
	v_mfma_f32_16x16x32_bf16 v[124:127], v[148:151], v[164:167], v[124:127]
	v_mfma_f32_16x16x32_bf16 v[120:123], v[156:159], v[164:167], v[120:123]
	v_mfma_f32_16x16x32_bf16 v[112:115], v[148:151], v[172:175], v[112:115]
	v_mfma_f32_16x16x32_bf16 v[104:107], v[156:159], v[172:175], v[104:107]
	v_mfma_f32_16x16x32_bf16 v[96:99], v[148:151], v[180:183], v[96:99]
	v_mfma_f32_16x16x32_bf16 v[88:91], v[156:159], v[180:183], v[88:91]
	v_mfma_f32_16x16x32_bf16 v[80:83], v[148:151], v[188:191], v[80:83]
	v_mfma_f32_16x16x32_bf16 v[72:75], v[156:159], v[188:191], v[72:75]
	s_setprio 0
	s_barrier
; #define PG8_STAGE(bufoff, gbase, voff) do { _Pragma("unroll") for (int _i = 0; _i < 2; ++_i) \
;         __builtin_amdgcn_global_load_lds((const unsigned*)((const char*)(gbase) + (voff)[_i]), (PG8_LAS unsigned*)(lds + (bufoff) + ldsw + _i * 8192), 16, 0, 0); } while (0)
; #define PG8_LDA(dst, b, h) do { _Pragma("unroll") for (int m = 0; m < 4; ++m) _Pragma("unroll") for (int k = 0; k < 2; ++k) dst[m][k] = *(const PG8_LAS bf16x8*)(lds + PG8_SA(b, h) + aoff + m * 2048 + k * 1024); } while (0)
; #define PG8_LDB(dst, b, h) do { _Pragma("unroll") for (int n = 0; n < 2; ++n) _Pragma("unroll") for (int k = 0; k < 2; ++k) dst[n][k] = *(const PG8_LAS bf16x8*)(lds + PG8_SB(b, h) + boff + n * 2048 + k * 1024); } while (0)
; #define PG8_MMA(ai, bj, At, Bt) do { __builtin_amdgcn_s_setprio(1); _Pragma("unroll") for (int m = 0; m < 4; ++m) _Pragma("unroll") for (int n = 0; n < 2; ++n) _Pragma("unroll") for (int k = 0; k < 2; ++k) \
;         acc[ai][bj][m][n] = __builtin_amdgcn_mfma_f32_16x16x32_bf16(Bt[n][k], At[m][k], acc[ai][bj][m][n], 0, 0, 0); __builtin_amdgcn_s_setprio(0); } while (0)
; #define PG8_WAIT_V(n) asm volatile("s_waitcnt vmcnt(" #n ")" ::: "memory")
; #define PG8_WAIT_L(n) asm volatile("s_waitcnt lgkmcnt(" #n ")" ::: "memory")
; #define PG8_BAR __builtin_amdgcn_s_barrier()
; #define PG8_SCHED __builtin_amdgcn_sched_barrier(0)
; template <class Epi, class Sched, bool ALIGN_EPI = false, bool SP2 = false>
; __device__ __forceinline__ void gemm_phase(PG8_LAS unsigned char* lds, const Gemm g, const Sched& S, const Epi& E, const int wave0) {
;     ...
;             PG8_LDB(B0, 1, 0); PG8_LDB(B1, 1, 1); PG8_SCHED; PG8_LDA(At, 1, 0); PG8_STAGE(PG8_SA(0, 1), a2 + hstep, voffA);
;             PG8_WAIT_V(8); PG8_WAIT_L(0); PG8_BAR; PG8_MMA(0, 0, At, B0); PG8_MMA(0, 1, At, B1); PG8_BAR; PG8_SCHED;
;             PG8_LDA(At, 1, 1); PG8_STAGE(PG8_SB(1, 0), b3, voffB); PG8_STAGE(PG8_SB(1, 1), b3 + hstep, voffB); PG8_STAGE(PG8_SA(1, 0), a3, voffA);
;             PG8_WAIT_V(8); PG8_WAIT_L(0); PG8_BAR; PG8_MMA(1, 0, At, B0); PG8_MMA(1, 1, At, B1); PG8_BAR; PG8_SCHED;
	s_add_i32 s18, s64, s95
	s_add_i32 m0, s18, 0xffffff80
	ds_read_b128 v[160:163], v245 offset:49152
	ds_read_b128 v[164:167], v245 offset:50176
	ds_read_b128 v[168:171], v245 offset:51200
	ds_read_b128 v[172:175], v245 offset:52224
	ds_read_b128 v[176:179], v245 offset:53248
	ds_read_b128 v[180:183], v245 offset:54272
	ds_read_b128 v[184:187], v245 offset:55296
	ds_read_b128 v[188:191], v245 offset:56320
	global_load_lds_dwordx4 v218, s[56:57] offset:128
	s_add_i32 m0, s18, 0x1f80
	s_add_u32 s18, s56, 0x40080
	s_addc_u32 s19, s57, 0
	global_load_lds_dwordx4 v222, s[56:57] offset:128
	s_add_i32 s56, s65, s95
	s_mov_b32 m0, s56
	s_nop 0
	global_load_lds_dwordx4 v218, s[18:19]
	s_add_i32 m0, s56, 0x2000
	s_nop 0
	global_load_lds_dwordx4 v222, s[18:19]
	s_add_i32 m0, s17, 0xffffff80
	s_nop 0
	global_load_lds_dwordx4 v216, s[58:59] offset:128
	s_add_i32 m0, s23, 0xffffff80
	s_nop 0
	global_load_lds_dwordx4 v220, s[58:59] offset:128
	s_waitcnt vmcnt(8)
	s_waitcnt lgkmcnt(0)
	s_barrier
	s_setprio 1
	v_mfma_f32_16x16x32_bf16 v[60:63], v[64:67], v[160:163], v[60:63]
	v_mfma_f32_16x16x32_bf16 v[52:55], v[136:139], v[160:163], v[52:55]
	v_mfma_f32_16x16x32_bf16 v[44:47], v[64:67], v[168:171], v[44:47]
	v_mfma_f32_16x16x32_bf16 v[36:39], v[136:139], v[168:171], v[36:39]
	v_mfma_f32_16x16x32_bf16 v[28:31], v[64:67], v[176:179], v[28:31]
	v_mfma_f32_16x16x32_bf16 v[20:23], v[136:139], v[176:179], v[20:23]
	v_mfma_f32_16x16x32_bf16 v[12:15], v[64:67], v[184:187], v[12:15]
	v_mfma_f32_16x16x32_bf16 v[4:7], v[136:139], v[184:187], v[4:7]
	v_mfma_f32_16x16x32_bf16 v[60:63], v[68:71], v[164:167], v[60:63]
	v_mfma_f32_16x16x32_bf16 v[52:55], v[140:143], v[164:167], v[52:55]
	v_mfma_f32_16x16x32_bf16 v[44:47], v[68:71], v[172:175], v[44:47]
	v_mfma_f32_16x16x32_bf16 v[36:39], v[140:143], v[172:175], v[36:39]
	v_mfma_f32_16x16x32_bf16 v[28:31], v[68:71], v[180:183], v[28:31]
	v_mfma_f32_16x16x32_bf16 v[20:23], v[140:143], v[180:183], v[20:23]
	v_mfma_f32_16x16x32_bf16 v[12:15], v[68:71], v[188:191], v[12:15]
	v_mfma_f32_16x16x32_bf16 v[4:7], v[140:143], v[188:191], v[4:7]
	v_mfma_f32_16x16x32_bf16 v[56:59], v[144:147], v[160:163], v[56:59]
	v_mfma_f32_16x16x32_bf16 v[48:51], v[152:155], v[160:163], v[48:51]
	v_mfma_f32_16x16x32_bf16 v[40:43], v[144:147], v[168:171], v[40:43]
	v_mfma_f32_16x16x32_bf16 v[32:35], v[152:155], v[168:171], v[32:35]
	v_mfma_f32_16x16x32_bf16 v[24:27], v[144:147], v[176:179], v[24:27]
	v_mfma_f32_16x16x32_bf16 v[16:19], v[152:155], v[176:179], v[16:19]
	v_mfma_f32_16x16x32_bf16 v[8:11], v[144:147], v[184:187], v[8:11]
	v_mfma_f32_16x16x32_bf16 v[0:3], v[152:155], v[184:187], v[0:3]
	v_mfma_f32_16x16x32_bf16 v[56:59], v[148:151], v[164:167], v[56:59]
	v_mfma_f32_16x16x32_bf16 v[48:51], v[156:159], v[164:167], v[48:51]
	v_mfma_f32_16x16x32_bf16 v[40:43], v[148:151], v[172:175], v[40:43]
	v_mfma_f32_16x16x32_bf16 v[32:35], v[156:159], v[172:175], v[32:35]
	v_mfma_f32_16x16x32_bf16 v[24:27], v[148:151], v[180:183], v[24:27]
	v_mfma_f32_16x16x32_bf16 v[16:19], v[156:159], v[180:183], v[16:19]
	v_mfma_f32_16x16x32_bf16 v[8:11], v[148:151], v[188:191], v[8:11]
	v_mfma_f32_16x16x32_bf16 v[0:3], v[156:159], v[188:191], v[0:3]
	s_setprio 0
	s_barrier
	s_add_i32 s63, s63, 2
	s_add_u32 s10, s10, 0x100
	s_addc_u32 s11, s11, 0
	s_add_u32 s61, s61, 0x100
	s_addc_u32 s62, s62, 0
	s_cmp_gt_u32 s63, 13
